# fb_prompt epilogue: 32 dwordx2 stores widened to 16 dwordx4 with v_permlane32_swap pairs (doc 7.3); placement preserved
# baseline (speedup 1.0000x reference)
.LBB0_16:
	v_ashrrev_i32_e32 v0, 3, v143
	v_lshrrev_b32_e32 v1, 29, v0
	v_add_lshl_u32 v1, v0, v1, 3
	v_and_b32_e32 v1, 0xffffffc0, v1
	v_and_b32_e32 v2, 56, v211
	v_and_b32_e32 v0, 7, v0
	v_or3_b32 v190, v1, v2, v0
	v_ashrrev_i32_e32 v191, 31, v190
	v_lshlrev_b64 v[188:189], 8, v[190:191]
	v_or_b32_e32 v0, v188, v144
	v_mov_b32_e32 v1, v189
	v_lshlrev_b64 v[0:1], 9, v[0:1]
	v_lshl_add_u64 v[198:199], v[146:147], 0, v[0:1]
	v_or_b32_e32 v0, v188, v148
	v_mov_b32_e32 v1, v189
	v_lshlrev_b64 v[0:1], 9, v[0:1]
	v_lshl_add_u64 v[196:197], v[146:147], 0, v[0:1]
	v_or_b32_e32 v0, v188, v150
	v_mov_b32_e32 v1, v189
	v_lshlrev_b64 v[0:1], 9, v[0:1]
	v_lshl_add_u64 v[194:195], v[146:147], 0, v[0:1]
	v_or_b32_e32 v0, v188, v152
	v_mov_b32_e32 v1, v189
	v_lshlrev_b64 v[0:1], 9, v[0:1]
	v_lshl_add_u64 v[192:193], v[146:147], 0, v[0:1]
	global_load_dwordx4 v[0:3], v[198:199], off
	v_and_or_b32 v128, v188, s16, v158
	v_lshlrev_b32_e32 v128, 1, v128
	v_add_u32_e32 v143, s23, v143
	s_movk_i32 s0, 0x1ff
	v_cmp_lt_i32_e32 vcc, s0, v143
	v_add_u32_e32 v211, s20, v211
	s_or_b64 s[12:13], vcc, s[12:13]
	s_waitcnt vmcnt(0)
	ds_write_b128 v145, v[0:3]
	global_load_dwordx4 v[0:3], v[196:197], off
	s_waitcnt vmcnt(0)
	ds_write_b128 v149, v[0:3]
	global_load_dwordx4 v[0:3], v[194:195], off
	s_waitcnt vmcnt(0)
	ds_write_b128 v151, v[0:3]
	global_load_dwordx4 v[0:3], v[192:193], off
	s_waitcnt vmcnt(0)
	ds_write_b128 v153, v[0:3]
	global_load_dwordx4 v[0:3], v[154:155], off
	s_waitcnt vmcnt(0)
	ds_write_b128 v159, v[0:3]
	global_load_dwordx4 v[0:3], v[156:157], off
	s_waitcnt vmcnt(0)
	ds_write_b128 v200, v[0:3]
	s_waitcnt lgkmcnt(0)
	s_barrier
	ds_read_b128 v[0:3], v203 offset:2560
	ds_read_b128 v[4:7], v203 offset:5120
	ds_read_b128 v[8:11], v203 offset:7680
	ds_read_b128 v[12:15], v204 offset:23040
	ds_read_b128 v[16:19], v203
	ds_read_b128 v[130:133], v203 offset:32
	ds_read_b128 v[64:67], v204 offset:20480
	ds_read_b128 v[134:137], v204 offset:20512
	s_waitcnt lgkmcnt(1)
	v_mfma_f32_32x32x16_bf16 v[112:127], v[16:19], v[64:67], 0
	ds_read_b128 v[212:215], v203 offset:2592
	ds_read_b128 v[216:219], v203 offset:5152
	ds_read_b128 v[220:223], v203 offset:7712
	ds_read_b128 v[224:227], v204 offset:23072
	v_mfma_f32_32x32x16_bf16 v[48:63], v[16:19], v[12:15], 0
	s_waitcnt lgkmcnt(4)
	v_mfma_f32_32x32x16_bf16 v[112:127], v[130:133], v[134:137], v[112:127]
	s_waitcnt lgkmcnt(0)
	v_mfma_f32_32x32x16_bf16 v[48:63], v[130:133], v[224:227], v[48:63]
	global_load_dwordx4 v[130:133], v[198:199], off offset:64
	s_waitcnt vmcnt(0)
	ds_write_b128 v205, v[130:133]
	global_load_dwordx4 v[130:133], v[196:197], off offset:64
	v_mfma_f32_32x32x16_bf16 v[96:111], v[0:3], v[64:67], 0
	s_waitcnt vmcnt(0)
	ds_write_b128 v206, v[130:133]
	global_load_dwordx4 v[130:133], v[194:195], off offset:64
	v_mfma_f32_32x32x16_bf16 v[32:47], v[0:3], v[12:15], 0
	s_waitcnt vmcnt(0)
	ds_write_b128 v207, v[130:133]
	global_load_dwordx4 v[130:133], v[192:193], off offset:64
	v_mfma_f32_32x32x16_bf16 v[80:95], v[4:7], v[64:67], 0
	s_waitcnt vmcnt(0)
	ds_write_b128 v208, v[130:133]
	global_load_dwordx4 v[130:133], v[160:161], off
	v_mfma_f32_32x32x16_bf16 v[16:31], v[4:7], v[12:15], 0
	s_waitcnt vmcnt(0)
	ds_write_b128 v209, v[130:133]
	global_load_dwordx4 v[130:133], v[162:163], off
	v_mfma_f32_32x32x16_bf16 v[64:79], v[8:11], v[64:67], 0
	s_waitcnt vmcnt(0)
	ds_write_b128 v210, v[130:133]
	v_mfma_f32_32x32x16_bf16 v[0:15], v[8:11], v[12:15], 0
	s_waitcnt lgkmcnt(0)
	s_barrier
	v_mfma_f32_32x32x16_bf16 v[96:111], v[212:215], v[134:137], v[96:111]
	v_mfma_f32_32x32x16_bf16 v[32:47], v[212:215], v[224:227], v[32:47]
	v_mfma_f32_32x32x16_bf16 v[80:95], v[216:219], v[134:137], v[80:95]
	v_mfma_f32_32x32x16_bf16 v[16:31], v[216:219], v[224:227], v[16:31]
	v_mfma_f32_32x32x16_bf16 v[64:79], v[220:223], v[134:137], v[64:79]
	v_mfma_f32_32x32x16_bf16 v[0:15], v[220:223], v[224:227], v[0:15]
	ds_read_b128 v[130:133], v203 offset:33280
	ds_read_b128 v[134:137], v203 offset:35840
	ds_read_b128 v[212:215], v203 offset:38400
	ds_read_b128 v[216:219], v204 offset:53760
	ds_read_b128 v[220:223], v203 offset:30720
	ds_read_b128 v[224:227], v203 offset:30752
	ds_read_b128 v[228:231], v204 offset:51200
	ds_read_b128 v[236:239], v204 offset:51232
	s_waitcnt lgkmcnt(1)
	v_mfma_f32_32x32x16_bf16 v[96:111], v[130:133], v[228:231], v[96:111]
	v_mfma_f32_32x32x16_bf16 v[32:47], v[130:133], v[216:219], v[32:47]
	v_mfma_f32_32x32x16_bf16 v[48:63], v[220:223], v[216:219], v[48:63]
	v_mfma_f32_32x32x16_bf16 v[80:95], v[134:137], v[228:231], v[80:95]
	v_mfma_f32_32x32x16_bf16 v[16:31], v[134:137], v[216:219], v[16:31]
	v_mfma_f32_32x32x16_bf16 v[64:79], v[212:215], v[228:231], v[64:79]
	v_mfma_f32_32x32x16_bf16 v[0:15], v[212:215], v[216:219], v[0:15]
	ds_read_b128 v[130:133], v203 offset:33312
	ds_read_b128 v[134:137], v203 offset:35872
	ds_read_b128 v[212:215], v203 offset:38432
	ds_read_b128 v[216:219], v204 offset:53792
	s_waitcnt lgkmcnt(3)
	v_mfma_f32_32x32x16_bf16 v[96:111], v[130:133], v[236:239], v[96:111]
	s_waitcnt lgkmcnt(0)
	v_mfma_f32_32x32x16_bf16 v[32:47], v[130:133], v[216:219], v[32:47]
	global_load_dwordx4 v[130:133], v[198:199], off offset:128
	s_waitcnt vmcnt(0)
	ds_write_b128 v145, v[130:133]
	global_load_dwordx4 v[130:133], v[196:197], off offset:128
	v_mfma_f32_32x32x16_bf16 v[112:127], v[220:223], v[228:231], v[112:127]
	s_waitcnt vmcnt(0)
	ds_write_b128 v149, v[130:133]
	global_load_dwordx4 v[130:133], v[194:195], off offset:128
	v_mfma_f32_32x32x16_bf16 v[48:63], v[224:227], v[216:219], v[48:63]
	s_waitcnt vmcnt(0)
	ds_write_b128 v151, v[130:133]
	global_load_dwordx4 v[130:133], v[192:193], off offset:128
	v_mfma_f32_32x32x16_bf16 v[80:95], v[134:137], v[236:239], v[80:95]
	s_waitcnt vmcnt(0)
	ds_write_b128 v153, v[130:133]
	global_load_dwordx4 v[130:133], v[164:165], off
	v_mfma_f32_32x32x16_bf16 v[16:31], v[134:137], v[216:219], v[16:31]
	s_waitcnt vmcnt(0)
	ds_write_b128 v159, v[130:133]
	global_load_dwordx4 v[130:133], v[166:167], off
	v_mfma_f32_32x32x16_bf16 v[64:79], v[212:215], v[236:239], v[64:79]
	s_waitcnt vmcnt(0)
	ds_write_b128 v200, v[130:133]
	v_mfma_f32_32x32x16_bf16 v[0:15], v[212:215], v[216:219], v[0:15]
	s_waitcnt lgkmcnt(0)
	s_barrier
	v_mfma_f32_32x32x16_bf16 v[112:127], v[224:227], v[236:239], v[112:127]
	ds_read_b128 v[130:133], v203 offset:2560
	ds_read_b128 v[134:137], v203 offset:5120
	ds_read_b128 v[212:215], v203 offset:7680
	ds_read_b128 v[216:219], v204 offset:23040
	ds_read_b128 v[220:223], v203
	ds_read_b128 v[224:227], v203 offset:32
	ds_read_b128 v[228:231], v204 offset:20480
	ds_read_b128 v[236:239], v204 offset:20512
	s_waitcnt lgkmcnt(1)
	v_mfma_f32_32x32x16_bf16 v[96:111], v[130:133], v[228:231], v[96:111]
	v_mfma_f32_32x32x16_bf16 v[32:47], v[130:133], v[216:219], v[32:47]
	v_mfma_f32_32x32x16_bf16 v[48:63], v[220:223], v[216:219], v[48:63]
	v_mfma_f32_32x32x16_bf16 v[80:95], v[134:137], v[228:231], v[80:95]
	v_mfma_f32_32x32x16_bf16 v[16:31], v[134:137], v[216:219], v[16:31]
	v_mfma_f32_32x32x16_bf16 v[64:79], v[212:215], v[228:231], v[64:79]
	v_mfma_f32_32x32x16_bf16 v[0:15], v[212:215], v[216:219], v[0:15]
	ds_read_b128 v[130:133], v203 offset:2592
	ds_read_b128 v[134:137], v203 offset:5152
	ds_read_b128 v[212:215], v203 offset:7712
	ds_read_b128 v[216:219], v204 offset:23072
	s_waitcnt lgkmcnt(3)
	v_mfma_f32_32x32x16_bf16 v[96:111], v[130:133], v[236:239], v[96:111]
	s_waitcnt lgkmcnt(0)
	v_mfma_f32_32x32x16_bf16 v[32:47], v[130:133], v[216:219], v[32:47]
	global_load_dwordx4 v[130:133], v[198:199], off offset:192
	s_waitcnt vmcnt(0)
	ds_write_b128 v205, v[130:133]
	global_load_dwordx4 v[130:133], v[196:197], off offset:192
	v_mfma_f32_32x32x16_bf16 v[112:127], v[220:223], v[228:231], v[112:127]
	s_waitcnt vmcnt(0)
	ds_write_b128 v206, v[130:133]
	global_load_dwordx4 v[130:133], v[194:195], off offset:192
	v_mfma_f32_32x32x16_bf16 v[48:63], v[224:227], v[216:219], v[48:63]
	s_waitcnt vmcnt(0)
	ds_write_b128 v207, v[130:133]
	global_load_dwordx4 v[130:133], v[192:193], off offset:192
	v_mfma_f32_32x32x16_bf16 v[80:95], v[134:137], v[236:239], v[80:95]
	s_waitcnt vmcnt(0)
	ds_write_b128 v208, v[130:133]
	global_load_dwordx4 v[130:133], v[168:169], off
	v_mfma_f32_32x32x16_bf16 v[16:31], v[134:137], v[216:219], v[16:31]
	s_waitcnt vmcnt(0)
	ds_write_b128 v209, v[130:133]
	global_load_dwordx4 v[130:133], v[170:171], off
	v_mfma_f32_32x32x16_bf16 v[64:79], v[212:215], v[236:239], v[64:79]
	s_waitcnt vmcnt(0)
	ds_write_b128 v210, v[130:133]
	v_mfma_f32_32x32x16_bf16 v[0:15], v[212:215], v[216:219], v[0:15]
	s_waitcnt lgkmcnt(0)
	s_barrier
	v_mfma_f32_32x32x16_bf16 v[112:127], v[224:227], v[236:239], v[112:127]
	ds_read_b128 v[130:133], v203 offset:33280
	ds_read_b128 v[134:137], v203 offset:35840
	ds_read_b128 v[212:215], v203 offset:38400
	ds_read_b128 v[216:219], v204 offset:53760
	ds_read_b128 v[220:223], v203 offset:30720
	ds_read_b128 v[224:227], v203 offset:30752
	ds_read_b128 v[228:231], v204 offset:51200
	ds_read_b128 v[236:239], v204 offset:51232
	s_waitcnt lgkmcnt(1)
	v_mfma_f32_32x32x16_bf16 v[96:111], v[130:133], v[228:231], v[96:111]
	v_mfma_f32_32x32x16_bf16 v[32:47], v[130:133], v[216:219], v[32:47]
	v_mfma_f32_32x32x16_bf16 v[48:63], v[220:223], v[216:219], v[48:63]
	v_mfma_f32_32x32x16_bf16 v[80:95], v[134:137], v[228:231], v[80:95]
	v_mfma_f32_32x32x16_bf16 v[16:31], v[134:137], v[216:219], v[16:31]
	v_mfma_f32_32x32x16_bf16 v[64:79], v[212:215], v[228:231], v[64:79]
	v_mfma_f32_32x32x16_bf16 v[0:15], v[212:215], v[216:219], v[0:15]
	ds_read_b128 v[130:133], v203 offset:33312
	ds_read_b128 v[134:137], v203 offset:35872
	ds_read_b128 v[212:215], v203 offset:38432
	ds_read_b128 v[216:219], v204 offset:53792
	s_waitcnt lgkmcnt(3)
	v_mfma_f32_32x32x16_bf16 v[96:111], v[130:133], v[236:239], v[96:111]
	s_waitcnt lgkmcnt(0)
	v_mfma_f32_32x32x16_bf16 v[32:47], v[130:133], v[216:219], v[32:47]
	global_load_dwordx4 v[130:133], v[198:199], off offset:256
	s_waitcnt vmcnt(0)
	ds_write_b128 v145, v[130:133]
	global_load_dwordx4 v[130:133], v[196:197], off offset:256
	v_mfma_f32_32x32x16_bf16 v[112:127], v[220:223], v[228:231], v[112:127]
	s_waitcnt vmcnt(0)
	ds_write_b128 v149, v[130:133]
	global_load_dwordx4 v[130:133], v[194:195], off offset:256
	v_mfma_f32_32x32x16_bf16 v[48:63], v[224:227], v[216:219], v[48:63]
	s_waitcnt vmcnt(0)
	ds_write_b128 v151, v[130:133]
	global_load_dwordx4 v[130:133], v[192:193], off offset:256
	v_mfma_f32_32x32x16_bf16 v[80:95], v[134:137], v[236:239], v[80:95]
	s_waitcnt vmcnt(0)
	ds_write_b128 v153, v[130:133]
	global_load_dwordx4 v[130:133], v[172:173], off
	v_mfma_f32_32x32x16_bf16 v[16:31], v[134:137], v[216:219], v[16:31]
	s_waitcnt vmcnt(0)
	ds_write_b128 v159, v[130:133]
	global_load_dwordx4 v[130:133], v[174:175], off
	v_mfma_f32_32x32x16_bf16 v[64:79], v[212:215], v[236:239], v[64:79]
	s_waitcnt vmcnt(0)
	ds_write_b128 v200, v[130:133]
	v_mfma_f32_32x32x16_bf16 v[0:15], v[212:215], v[216:219], v[0:15]
	s_waitcnt lgkmcnt(0)
	s_barrier
	v_mfma_f32_32x32x16_bf16 v[112:127], v[224:227], v[236:239], v[112:127]
	ds_read_b128 v[130:133], v203 offset:2560
	ds_read_b128 v[134:137], v203 offset:5120
	ds_read_b128 v[212:215], v203 offset:7680
	ds_read_b128 v[216:219], v204 offset:23040
	ds_read_b128 v[220:223], v203
	ds_read_b128 v[224:227], v203 offset:32
	ds_read_b128 v[228:231], v204 offset:20480
	ds_read_b128 v[236:239], v204 offset:20512
	s_waitcnt lgkmcnt(1)
	v_mfma_f32_32x32x16_bf16 v[96:111], v[130:133], v[228:231], v[96:111]
	v_mfma_f32_32x32x16_bf16 v[32:47], v[130:133], v[216:219], v[32:47]
	v_mfma_f32_32x32x16_bf16 v[48:63], v[220:223], v[216:219], v[48:63]
	v_mfma_f32_32x32x16_bf16 v[80:95], v[134:137], v[228:231], v[80:95]
	v_mfma_f32_32x32x16_bf16 v[16:31], v[134:137], v[216:219], v[16:31]
	v_mfma_f32_32x32x16_bf16 v[64:79], v[212:215], v[228:231], v[64:79]
	v_mfma_f32_32x32x16_bf16 v[0:15], v[212:215], v[216:219], v[0:15]
	ds_read_b128 v[130:133], v203 offset:2592
	ds_read_b128 v[134:137], v203 offset:5152
	ds_read_b128 v[212:215], v203 offset:7712
	ds_read_b128 v[216:219], v204 offset:23072
	s_waitcnt lgkmcnt(3)
	v_mfma_f32_32x32x16_bf16 v[96:111], v[130:133], v[236:239], v[96:111]
	s_waitcnt lgkmcnt(0)
	v_mfma_f32_32x32x16_bf16 v[32:47], v[130:133], v[216:219], v[32:47]
	global_load_dwordx4 v[130:133], v[198:199], off offset:320
	s_waitcnt vmcnt(0)
	ds_write_b128 v205, v[130:133]
	global_load_dwordx4 v[130:133], v[196:197], off offset:320
	v_mfma_f32_32x32x16_bf16 v[112:127], v[220:223], v[228:231], v[112:127]
	s_waitcnt vmcnt(0)
	ds_write_b128 v206, v[130:133]
	global_load_dwordx4 v[130:133], v[194:195], off offset:320
	v_mfma_f32_32x32x16_bf16 v[48:63], v[224:227], v[216:219], v[48:63]
	s_waitcnt vmcnt(0)
	ds_write_b128 v207, v[130:133]
	global_load_dwordx4 v[130:133], v[192:193], off offset:320
	v_mfma_f32_32x32x16_bf16 v[80:95], v[134:137], v[236:239], v[80:95]
	s_waitcnt vmcnt(0)
	ds_write_b128 v208, v[130:133]
	global_load_dwordx4 v[130:133], v[176:177], off
	v_mfma_f32_32x32x16_bf16 v[16:31], v[134:137], v[216:219], v[16:31]
	s_waitcnt vmcnt(0)
	ds_write_b128 v209, v[130:133]
	global_load_dwordx4 v[130:133], v[178:179], off
	v_mfma_f32_32x32x16_bf16 v[64:79], v[212:215], v[236:239], v[64:79]
	s_waitcnt vmcnt(0)
	ds_write_b128 v210, v[130:133]
	v_mfma_f32_32x32x16_bf16 v[0:15], v[212:215], v[216:219], v[0:15]
	s_waitcnt lgkmcnt(0)
	s_barrier
	v_mfma_f32_32x32x16_bf16 v[112:127], v[224:227], v[236:239], v[112:127]
	ds_read_b128 v[130:133], v203 offset:33280
	ds_read_b128 v[134:137], v203 offset:35840
	ds_read_b128 v[212:215], v203 offset:38400
	ds_read_b128 v[216:219], v204 offset:53760
	ds_read_b128 v[220:223], v203 offset:30720
	ds_read_b128 v[224:227], v203 offset:30752
	ds_read_b128 v[228:231], v204 offset:51200
	ds_read_b128 v[236:239], v204 offset:51232
	s_waitcnt lgkmcnt(1)
	v_mfma_f32_32x32x16_bf16 v[96:111], v[130:133], v[228:231], v[96:111]
	v_mfma_f32_32x32x16_bf16 v[32:47], v[130:133], v[216:219], v[32:47]
	v_mfma_f32_32x32x16_bf16 v[48:63], v[220:223], v[216:219], v[48:63]
	v_mfma_f32_32x32x16_bf16 v[80:95], v[134:137], v[228:231], v[80:95]
	v_mfma_f32_32x32x16_bf16 v[16:31], v[134:137], v[216:219], v[16:31]
	v_mfma_f32_32x32x16_bf16 v[64:79], v[212:215], v[228:231], v[64:79]
	v_mfma_f32_32x32x16_bf16 v[0:15], v[212:215], v[216:219], v[0:15]
	ds_read_b128 v[130:133], v203 offset:33312
	ds_read_b128 v[134:137], v203 offset:35872
	ds_read_b128 v[212:215], v203 offset:38432
	ds_read_b128 v[216:219], v204 offset:53792
	s_waitcnt lgkmcnt(3)
	v_mfma_f32_32x32x16_bf16 v[96:111], v[130:133], v[236:239], v[96:111]
	s_waitcnt lgkmcnt(0)
	v_mfma_f32_32x32x16_bf16 v[32:47], v[130:133], v[216:219], v[32:47]
	global_load_dwordx4 v[130:133], v[198:199], off offset:384
	s_waitcnt vmcnt(0)
	ds_write_b128 v145, v[130:133]
	global_load_dwordx4 v[130:133], v[196:197], off offset:384
	v_mfma_f32_32x32x16_bf16 v[112:127], v[220:223], v[228:231], v[112:127]
	s_waitcnt vmcnt(0)
	ds_write_b128 v149, v[130:133]
	global_load_dwordx4 v[130:133], v[194:195], off offset:384
	v_mfma_f32_32x32x16_bf16 v[48:63], v[224:227], v[216:219], v[48:63]
	s_waitcnt vmcnt(0)
	ds_write_b128 v151, v[130:133]
	global_load_dwordx4 v[130:133], v[192:193], off offset:384
	v_mfma_f32_32x32x16_bf16 v[80:95], v[134:137], v[236:239], v[80:95]
	s_waitcnt vmcnt(0)
	ds_write_b128 v153, v[130:133]
	global_load_dwordx4 v[130:133], v[180:181], off
	v_mfma_f32_32x32x16_bf16 v[16:31], v[134:137], v[216:219], v[16:31]
	s_waitcnt vmcnt(0)
	ds_write_b128 v159, v[130:133]
	global_load_dwordx4 v[130:133], v[182:183], off
	v_mfma_f32_32x32x16_bf16 v[64:79], v[212:215], v[236:239], v[64:79]
	s_waitcnt vmcnt(0)
	ds_write_b128 v200, v[130:133]
	v_mfma_f32_32x32x16_bf16 v[0:15], v[212:215], v[216:219], v[0:15]
	s_waitcnt lgkmcnt(0)
	s_barrier
	v_mfma_f32_32x32x16_bf16 v[112:127], v[224:227], v[236:239], v[112:127]
	ds_read_b128 v[130:133], v203 offset:2560
	ds_read_b128 v[134:137], v203 offset:5120
	ds_read_b128 v[212:215], v203 offset:7680
	ds_read_b128 v[216:219], v204 offset:23040
	ds_read_b128 v[220:223], v203
	ds_read_b128 v[224:227], v203 offset:32
	ds_read_b128 v[228:231], v204 offset:20480
	ds_read_b128 v[236:239], v204 offset:20512
	s_waitcnt lgkmcnt(1)
	v_mfma_f32_32x32x16_bf16 v[96:111], v[130:133], v[228:231], v[96:111]
	v_mfma_f32_32x32x16_bf16 v[32:47], v[130:133], v[216:219], v[32:47]
	v_mfma_f32_32x32x16_bf16 v[48:63], v[220:223], v[216:219], v[48:63]
	v_mfma_f32_32x32x16_bf16 v[80:95], v[134:137], v[228:231], v[80:95]
	v_mfma_f32_32x32x16_bf16 v[16:31], v[134:137], v[216:219], v[16:31]
	v_mfma_f32_32x32x16_bf16 v[64:79], v[212:215], v[228:231], v[64:79]
	v_mfma_f32_32x32x16_bf16 v[0:15], v[212:215], v[216:219], v[0:15]
	ds_read_b128 v[130:133], v203 offset:2592
	ds_read_b128 v[134:137], v203 offset:5152
	ds_read_b128 v[212:215], v203 offset:7712
	ds_read_b128 v[216:219], v204 offset:23072
	s_waitcnt lgkmcnt(3)
	v_mfma_f32_32x32x16_bf16 v[96:111], v[130:133], v[236:239], v[96:111]
	s_waitcnt lgkmcnt(0)
	v_mfma_f32_32x32x16_bf16 v[32:47], v[130:133], v[216:219], v[32:47]
	global_load_dwordx4 v[130:133], v[198:199], off offset:448
	s_waitcnt vmcnt(0)
	ds_write_b128 v205, v[130:133]
	global_load_dwordx4 v[130:133], v[196:197], off offset:448
	v_mfma_f32_32x32x16_bf16 v[112:127], v[220:223], v[228:231], v[112:127]
	s_waitcnt vmcnt(0)
	ds_write_b128 v206, v[130:133]
	global_load_dwordx4 v[130:133], v[194:195], off offset:448
	v_mfma_f32_32x32x16_bf16 v[112:127], v[224:227], v[236:239], v[112:127]
	s_waitcnt vmcnt(0)
	ds_write_b128 v207, v[130:133]
	global_load_dwordx4 v[130:133], v[192:193], off offset:448
	v_mfma_f32_32x32x16_bf16 v[64:79], v[212:215], v[236:239], v[64:79]
	s_waitcnt vmcnt(0)
	ds_write_b128 v208, v[130:133]
	global_load_dwordx4 v[130:133], v[184:185], off
	v_mfma_f32_32x32x16_bf16 v[48:63], v[224:227], v[216:219], v[48:63]
	s_waitcnt vmcnt(0)
	ds_write_b128 v209, v[130:133]
	global_load_dwordx4 v[130:133], v[186:187], off
	v_mfma_f32_32x32x16_bf16 v[80:95], v[134:137], v[236:239], v[80:95]
	s_waitcnt vmcnt(0)
	ds_write_b128 v210, v[130:133]
	v_mfma_f32_32x32x16_bf16 v[16:31], v[134:137], v[216:219], v[16:31]
	s_waitcnt lgkmcnt(0)
	s_barrier
	v_mfma_f32_32x32x16_bf16 v[0:15], v[212:215], v[216:219], v[0:15]
	ds_read_b128 v[130:133], v203 offset:33280
	ds_read_b128 v[134:137], v203 offset:35840
	ds_read_b128 v[192:195], v203 offset:38400
	ds_read_b128 v[196:199], v204 offset:53760
	ds_read_b128 v[212:215], v203 offset:30720
	ds_read_b128 v[216:219], v203 offset:30752
	ds_read_b128 v[220:223], v204 offset:51200
	ds_read_b128 v[224:227], v204 offset:51232
	s_waitcnt lgkmcnt(1)
	v_mfma_f32_32x32x16_bf16 v[112:127], v[212:215], v[220:223], v[112:127]
	v_mfma_f32_32x32x16_bf16 v[64:79], v[192:195], v[220:223], v[64:79]
	v_mfma_f32_32x32x16_bf16 v[96:111], v[130:133], v[220:223], v[96:111]
	v_mfma_f32_32x32x16_bf16 v[32:47], v[130:133], v[196:199], v[32:47]
	v_mfma_f32_32x32x16_bf16 v[48:63], v[212:215], v[196:199], v[48:63]
	v_mfma_f32_32x32x16_bf16 v[80:95], v[134:137], v[220:223], v[80:95]
	v_mfma_f32_32x32x16_bf16 v[16:31], v[134:137], v[196:199], v[16:31]
	v_mfma_f32_32x32x16_bf16 v[0:15], v[192:195], v[196:199], v[0:15]
	ds_read_b128 v[130:133], v203 offset:33312
	ds_read_b128 v[134:137], v203 offset:35872
	ds_read_b128 v[192:195], v203 offset:38432
	ds_read_b128 v[196:199], v204 offset:53792
	s_waitcnt lgkmcnt(0)
	s_barrier
	v_mfma_f32_32x32x16_bf16 v[112:127], v[216:219], v[224:227], v[112:127]
	v_mfma_f32_32x32x16_bf16 v[64:79], v[192:195], v[224:227], v[64:79]
	v_mfma_f32_32x32x16_bf16 v[96:111], v[130:133], v[224:227], v[96:111]
	v_mfma_f32_32x32x16_bf16 v[32:47], v[130:133], v[196:199], v[32:47]
	v_mfma_f32_32x32x16_bf16 v[80:95], v[134:137], v[224:227], v[80:95]
	v_mfma_f32_32x32x16_bf16 v[48:63], v[216:219], v[196:199], v[48:63]
	v_mfma_f32_32x32x16_bf16 v[16:31], v[134:137], v[196:199], v[16:31]
	v_mfma_f32_32x32x16_bf16 v[0:15], v[192:195], v[196:199], v[0:15]
	s_branch .Lfbp_addr
	s_nop 0
	s_nop 0
	s_nop 0
	s_nop 0
	s_nop 0
	s_nop 0
	s_nop 0
	s_nop 0
	s_nop 0
	s_nop 0
	s_nop 0
	s_nop 0
	s_nop 0
	s_nop 0
	s_nop 0
	s_nop 0
	s_nop 0
	s_nop 0
.Lfbp_addrd:
	v_cvt_pk_bf16_f32 v112, v112, v113
	v_cvt_pk_bf16_f32 v113, v114, v115
	v_cvt_pk_bf16_f32 v114, v116, v117
	v_cvt_pk_bf16_f32 v115, v118, v119
	v_cvt_pk_bf16_f32 v120, v120, v121
	v_cvt_pk_bf16_f32 v121, v122, v123
	v_cvt_pk_bf16_f32 v122, v124, v125
	v_cvt_pk_bf16_f32 v123, v126, v127
	v_permlane32_swap_b32_e32 v112, v114
	v_permlane32_swap_b32_e32 v113, v115
	global_store_dwordx4 v[236:237], v[112:115], off
	v_cvt_pk_bf16_f32 v64, v64, v65
	v_cvt_pk_bf16_f32 v65, v66, v67
	v_cvt_pk_bf16_f32 v66, v68, v69
	v_cvt_pk_bf16_f32 v67, v70, v71
	v_permlane32_swap_b32_e32 v120, v122
	v_permlane32_swap_b32_e32 v121, v123
	global_store_dwordx4 v[236:237], v[120:123], off offset:32
	v_cvt_pk_bf16_f32 v72, v72, v73
	v_cvt_pk_bf16_f32 v73, v74, v75
	v_cvt_pk_bf16_f32 v74, v76, v77
	v_cvt_pk_bf16_f32 v75, v78, v79
	v_permlane32_swap_b32_e32 v64, v66
	v_permlane32_swap_b32_e32 v65, v67
	global_store_dwordx4 v[236:237], v[64:67], off offset:192
	v_cvt_pk_bf16_f32 v96, v96, v97
	v_cvt_pk_bf16_f32 v97, v98, v99
	v_cvt_pk_bf16_f32 v98, v100, v101
	v_cvt_pk_bf16_f32 v99, v102, v103
	v_permlane32_swap_b32_e32 v72, v74
	v_permlane32_swap_b32_e32 v73, v75
	global_store_dwordx4 v[236:237], v[72:75], off offset:224
	v_cvt_pk_bf16_f32 v104, v104, v105
	v_cvt_pk_bf16_f32 v105, v106, v107
	v_cvt_pk_bf16_f32 v106, v108, v109
	v_cvt_pk_bf16_f32 v107, v110, v111
	v_permlane32_swap_b32_e32 v96, v98
	v_permlane32_swap_b32_e32 v97, v99
	global_store_dwordx4 v[236:237], v[96:99], off offset:64
	v_cvt_pk_bf16_f32 v32, v32, v33
	v_cvt_pk_bf16_f32 v33, v34, v35
	v_cvt_pk_bf16_f32 v34, v36, v37
	v_cvt_pk_bf16_f32 v35, v38, v39
	v_permlane32_swap_b32_e32 v104, v106
	v_permlane32_swap_b32_e32 v105, v107
	global_store_dwordx4 v[236:237], v[104:107], off offset:96
	v_cvt_pk_bf16_f32 v40, v40, v41
	v_cvt_pk_bf16_f32 v41, v42, v43
	v_cvt_pk_bf16_f32 v42, v44, v45
	v_cvt_pk_bf16_f32 v43, v46, v47
	v_permlane32_swap_b32_e32 v32, v34
	v_permlane32_swap_b32_e32 v33, v35
	global_store_dwordx4 v[238:239], v[32:35], off offset:64
	v_cvt_pk_bf16_f32 v80, v80, v81
	v_cvt_pk_bf16_f32 v81, v82, v83
	v_cvt_pk_bf16_f32 v82, v84, v85
	v_cvt_pk_bf16_f32 v83, v86, v87
	v_permlane32_swap_b32_e32 v40, v42
	v_permlane32_swap_b32_e32 v41, v43
	global_store_dwordx4 v[238:239], v[40:43], off offset:96
	v_cvt_pk_bf16_f32 v88, v88, v89
	v_cvt_pk_bf16_f32 v89, v90, v91
	v_cvt_pk_bf16_f32 v90, v92, v93
	v_cvt_pk_bf16_f32 v91, v94, v95
	v_permlane32_swap_b32_e32 v80, v82
	v_permlane32_swap_b32_e32 v81, v83
	global_store_dwordx4 v[236:237], v[80:83], off offset:128
	v_cvt_pk_bf16_f32 v48, v48, v49
	v_cvt_pk_bf16_f32 v49, v50, v51
	v_cvt_pk_bf16_f32 v50, v52, v53
	v_cvt_pk_bf16_f32 v51, v54, v55
	v_permlane32_swap_b32_e32 v88, v90
	v_permlane32_swap_b32_e32 v89, v91
	global_store_dwordx4 v[236:237], v[88:91], off offset:160
	v_cvt_pk_bf16_f32 v56, v56, v57
	v_cvt_pk_bf16_f32 v57, v58, v59
	v_cvt_pk_bf16_f32 v58, v60, v61
	v_cvt_pk_bf16_f32 v59, v62, v63
	v_permlane32_swap_b32_e32 v48, v50
	v_permlane32_swap_b32_e32 v49, v51
	global_store_dwordx4 v[238:239], v[48:51], off
	v_cvt_pk_bf16_f32 v16, v16, v17
	v_cvt_pk_bf16_f32 v17, v18, v19
	v_cvt_pk_bf16_f32 v18, v20, v21
	v_cvt_pk_bf16_f32 v19, v22, v23
	v_permlane32_swap_b32_e32 v56, v58
	v_permlane32_swap_b32_e32 v57, v59
	global_store_dwordx4 v[238:239], v[56:59], off offset:32
	v_cvt_pk_bf16_f32 v24, v24, v25
	v_cvt_pk_bf16_f32 v25, v26, v27
	v_cvt_pk_bf16_f32 v26, v28, v29
	v_cvt_pk_bf16_f32 v27, v30, v31
	v_permlane32_swap_b32_e32 v16, v18
	v_permlane32_swap_b32_e32 v17, v19
	global_store_dwordx4 v[238:239], v[16:19], off offset:128
	v_cvt_pk_bf16_f32 v0, v0, v1
	v_cvt_pk_bf16_f32 v1, v2, v3
	v_cvt_pk_bf16_f32 v2, v4, v5
	v_cvt_pk_bf16_f32 v3, v6, v7
	v_permlane32_swap_b32_e32 v24, v26
	v_permlane32_swap_b32_e32 v25, v27
	global_store_dwordx4 v[238:239], v[24:27], off offset:160
	v_cvt_pk_bf16_f32 v8, v8, v9
	v_cvt_pk_bf16_f32 v9, v10, v11
	v_cvt_pk_bf16_f32 v10, v12, v13
	v_cvt_pk_bf16_f32 v11, v14, v15
	v_permlane32_swap_b32_e32 v0, v2
	v_permlane32_swap_b32_e32 v1, v3
	global_store_dwordx4 v[238:239], v[0:3], off offset:192
	v_permlane32_swap_b32_e32 v8, v10
	v_permlane32_swap_b32_e32 v9, v11
	global_store_dwordx4 v[238:239], v[8:11], off offset:224
	s_andn2_b64 exec, exec, s[12:13]
	s_cbranch_execnz .LBB0_16

.Lfbp_addr:
	v_alignbit_b32 v212, v191, v190, 2
	v_add_u32_e32 v214, v201, v212
	v_ashrrev_i32_e32 v215, 31, v214
	v_lshlrev_b64 v[236:237], 11, v[214:215]
	v_lshl_add_u64 v[236:237], s[6:7], 0, v[236:237]
	v_lshl_add_u64 v[236:237], v[236:237], 0, v[128:129]
	v_add_u32_e32 v214, v202, v212
	v_ashrrev_i32_e32 v215, 31, v214
	v_lshlrev_b64 v[238:239], 11, v[214:215]
	v_lshl_add_u64 v[238:239], s[6:7], 0, v[238:239]
	v_lshl_add_u64 v[238:239], v[238:239], 0, v[128:129]
	v_mbcnt_lo_u32_b32 v220, -1, 0
	v_mbcnt_hi_u32_b32 v220, -1, v220
	v_and_b32_e32 v220, 32, v220
	v_lshrrev_b32_e32 v220, 2, v220
	v_mov_b32_e32 v221, 0
	v_lshl_add_u64 v[236:237], v[236:237], 0, v[220:221]
	v_lshl_add_u64 v[238:239], v[238:239], 0, v[220:221]
	s_branch .Lfbp_addrd
